# v16 + P0 x->bf16 row loop de-serialised: 8 chunk loads issued together with counted vmcnt(7) instead of load/vmcnt(0)/store ladders
# speedup vs baseline: 1.0027x; 1.0027x over previous
.LBB0_751:
	v_add_co_u32_e32 v22, vcc, 0xfffff000, v6
	v_lshl_add_u64 v[18:19], s[24:25], 0, v[4:5]
	s_nop 0
	v_addc_co_u32_e32 v23, vcc, -1, v7, vcc
	s_waitcnt lgkmcnt(0)
	global_load_dwordx4 v[48:51], v[22:23], off offset:-3072
	global_load_dwordx4 v[52:55], v[22:23], off offset:-2048
	global_load_dwordx4 v[56:59], v[22:23], off offset:-1024
	global_load_dwordx4 v[60:63], v[6:7], off offset:-4096
	global_load_dwordx4 v[64:67], v[6:7], off offset:-3072
	global_load_dwordx4 v[68:71], v[6:7], off offset:-2048
	global_load_dwordx4 v[72:75], v[6:7], off offset:-1024
	global_load_dwordx4 v[76:79], v[6:7], off
	v_add_co_u32_e32 v46, vcc, s3, v18
	s_nop 1
	v_addc_co_u32_e32 v47, vcc, 0, v19, vcc
	s_waitcnt vmcnt(7)
	v_cvt_pk_bf16_f32 v80, v48, v49
	v_cvt_pk_bf16_f32 v81, v50, v51
	global_store_dwordx2 v[46:47], v[80:81], off
	v_mul_f32_e32 v15, v49, v49
	v_mul_f32_e32 v16, v51, v51
	v_fmac_f32_e32 v15, v48, v48
	v_fmac_f32_e32 v16, v50, v50
	v_add_f32_e32 v14, v15, v16
	s_waitcnt vmcnt(7)
	v_cvt_pk_bf16_f32 v82, v52, v53
	v_cvt_pk_bf16_f32 v83, v54, v55
	global_store_dwordx2 v[46:47], v[82:83], off offset:512
	v_mul_f32_e32 v15, v53, v53
	v_mul_f32_e32 v16, v55, v55
	v_fmac_f32_e32 v15, v52, v52
	v_fmac_f32_e32 v16, v54, v54
	v_add_f32_e32 v15, v15, v16
	v_add_f32_e32 v14, v14, v15
	s_waitcnt vmcnt(7)
	v_cvt_pk_bf16_f32 v84, v56, v57
	v_cvt_pk_bf16_f32 v85, v58, v59
	global_store_dwordx2 v[46:47], v[84:85], off offset:1024
	v_mul_f32_e32 v15, v57, v57
	v_mul_f32_e32 v16, v59, v59
	v_fmac_f32_e32 v15, v56, v56
	v_fmac_f32_e32 v16, v58, v58
	v_add_f32_e32 v15, v15, v16
	v_add_f32_e32 v14, v14, v15
	s_waitcnt vmcnt(7)
	v_cvt_pk_bf16_f32 v86, v60, v61
	v_cvt_pk_bf16_f32 v87, v62, v63
	global_store_dwordx2 v[46:47], v[86:87], off offset:1536
	v_mul_f32_e32 v15, v61, v61
	v_mul_f32_e32 v16, v63, v63
	v_fmac_f32_e32 v15, v60, v60
	v_fmac_f32_e32 v16, v62, v62
	v_add_f32_e32 v15, v15, v16
	v_add_f32_e32 v14, v14, v15
	s_waitcnt vmcnt(7)
	v_cvt_pk_bf16_f32 v88, v64, v65
	v_cvt_pk_bf16_f32 v89, v66, v67
	global_store_dwordx2 v[46:47], v[88:89], off offset:2048
	v_mul_f32_e32 v15, v65, v65
	v_mul_f32_e32 v16, v67, v67
	v_fmac_f32_e32 v15, v64, v64
	v_fmac_f32_e32 v16, v66, v66
	v_add_f32_e32 v15, v15, v16
	v_add_f32_e32 v14, v14, v15
	s_waitcnt vmcnt(7)
	v_cvt_pk_bf16_f32 v90, v68, v69
	v_cvt_pk_bf16_f32 v91, v70, v71
	global_store_dwordx2 v[46:47], v[90:91], off offset:2560
	v_mul_f32_e32 v15, v69, v69
	v_mul_f32_e32 v16, v71, v71
	v_fmac_f32_e32 v15, v68, v68
	v_fmac_f32_e32 v16, v70, v70
	v_add_f32_e32 v15, v15, v16
	v_add_f32_e32 v14, v14, v15
	s_waitcnt vmcnt(7)
	v_cvt_pk_bf16_f32 v92, v72, v73
	v_cvt_pk_bf16_f32 v93, v74, v75
	global_store_dwordx2 v[46:47], v[92:93], off offset:3072
	v_mul_f32_e32 v15, v73, v73
	v_mul_f32_e32 v16, v75, v75
	v_fmac_f32_e32 v15, v72, v72
	v_fmac_f32_e32 v16, v74, v74
	v_add_f32_e32 v15, v15, v16
	v_add_f32_e32 v14, v14, v15
	s_waitcnt vmcnt(7)
	v_cvt_pk_bf16_f32 v94, v76, v77
	v_cvt_pk_bf16_f32 v95, v78, v79
	global_store_dwordx2 v[46:47], v[94:95], off offset:3584
	v_mul_f32_e32 v15, v77, v77
	v_mul_f32_e32 v16, v79, v79
	v_fmac_f32_e32 v15, v76, v76
	v_fmac_f32_e32 v16, v78, v78
	v_add_f32_e32 v15, v15, v16
	v_add_f32_e32 v14, v14, v15
	ds_bpermute_b32 v15, v8, v14
	s_waitcnt lgkmcnt(0)
	v_add_f32_e32 v14, v14, v15
	ds_bpermute_b32 v15, v9, v14
	s_waitcnt lgkmcnt(0)
	v_add_f32_e32 v14, v14, v15
	ds_bpermute_b32 v15, v10, v14
	s_waitcnt lgkmcnt(0)
	v_add_f32_e32 v14, v14, v15
	ds_bpermute_b32 v15, v11, v14
	s_waitcnt lgkmcnt(0)
	v_add_f32_e32 v14, v14, v15
	ds_bpermute_b32 v15, v12, v14
	s_waitcnt lgkmcnt(0)
	v_add_f32_e32 v14, v14, v15
	ds_bpermute_b32 v15, v13, v14
	s_and_saveexec_b64 s[18:19], s[4:5]
	s_cbranch_execz .LBB0_750
	s_waitcnt lgkmcnt(0)
	v_add_f32_e32 v14, v14, v15
	v_lshl_add_u64 v[16:17], s[24:25], 0, v[2:3]
	v_cndmask_b32_e64 v14, 0, v14, s[6:7]
	global_store_dword v[16:17], v14, off
	s_branch .LBB0_750
